# scan: absolute stream addresses (no per-load 64-bit address math), packed f32 multiplies for B*w, log2e folded into the decay rate
# speedup vs baseline: 1.0483x; 1.0051x over previous
; #define LAS __attribute__((address_space(3)))
; template <bool DRY>
; __device__ __forceinline__ void ssd_chunk(SsdRegs& R, f32x4 (&st)[2], LAS unsigned char* L, bf16_t* BIG, const float* DT, float* SSQY, const SsdItem& I, int c, int tid, int lane, int wave, int li, int pi, int c16, int q4) {
;     ...
;     const float dtl = R.rdt;
;     float acs = dtl * I.Ah;
;     acs += dppz<0x111>(acs); acs += dppz<0x112>(acs); acs += dppz<0x114>(acs); acs += dppz<0x118>(acs);
;     acs += __builtin_bit_cast(float, __builtin_amdgcn_update_dpp(0, __builtin_bit_cast(int, acs), 0x142, 0xa, 0xf, false));
;     acs += __builtin_bit_cast(float, __builtin_amdgcn_update_dpp(0, __builtin_bit_cast(int, acs), 0x143, 0xc, 0xf, false));
;     const float tot = __builtin_bit_cast(float, __builtin_amdgcn_readlane(__builtin_bit_cast(int, acs), 63));
;     const float wl = dtl * __expf(tot - acs), etot = __expf(tot);
;     LAS unsigned char* SCW = L + SCT + wave * 512;
;     *(LAS float*)(SCW + lane * 4) = acs; *(LAS float*)(SCW + 256 + lane * 4) = dtl;
; #pragma unroll
;     for (int pt = 0; pt < 2; ++pt) { u32x2 w; w.x = pk2(st[pt][0], st[pt][1]); w.y = pk2(st[pt][2], st[pt][3]); *(LAS u32x2*)(L + SB + (16 * pt + c16) * PC + (16 * wave + 4 * q4) * 2) = w; }
; #pragma unroll
;     for (int i = 0; i < 2; ++i) {
;         const int id = tid + 512 * i; *(LAS u32x4*)(L + CS + (id >> 4) * PC + (id & 15) * 16) = (u32x4){R.rc[i].x, R.rc[i].y, R.rc[i].z, R.rc[i].w};
;         const int n8 = wave + 8 * i; *(LAS u32x4*)(L + BS + lane * PC + n8 * 16) = (u32x4){R.rb[i].x, R.rb[i].y, R.rb[i].z, R.rb[i].w};
;         float f[8]; unpack8(R.rb[i], f);
;         u32x4 bwv; bwv.x = pk2(f[0] * wl, f[1] * wl); bwv.y = pk2(f[2] * wl, f[3] * wl); bwv.z = pk2(f[4] * wl, f[5] * wl); bwv.w = pk2(f[6] * wl, f[7] * wl);
;         *(LAS u32x4*)(L + BW + lane * PB + n8 * 16) = bwv;
;     }
;     if (wave < 4) *(LAS u32x4*)(L + XI + lane * PX + wave * 16) = (u32x4){R.rx.x, R.rx.y, R.rx.z, R.rx.w};
;     const u32x2 zc = R.rz;
;     __syncthreads();
;     if (c + 2 < 64) ssd_load(R, BIG, DT, I, c + 2, wave);
; template <bool DRY>
; __device__ __forceinline__ void phase_ssd_scan(const Args& a, int j, unsigned char* lds_raw) {
;     ...
;         I.Ah = -__expf(A_log[I.h]); I.Dh = Dp[I.h];
; #pragma unroll
.LBB0_718:
	s_lshr_b32 s2, s73, 4
	s_and_b32 s74, s72, 7
	s_and_b32 s2, s2, 3
	s_lshl_b32 s75, s74, 4
	s_lshl_b32 s78, s2, 2
	s_lshr_b32 s3, s73, 3
	s_or_b32 s80, s78, s75
	s_sub_u32 s100, s101, 2
	s_lshl_b32 s80, s80, s100
	v_add_u32_e32 v54, s80, v109
	s_lshl_b32 s80, s74, 7
	s_and_b32 s3, s3, 1
	v_add_lshl_u32 v56, v1, s80, 1
	v_add_lshl_u32 v58, v118, s80, 1
	v_add_lshl_u32 v62, v120, s80, 1
	s_lshl_b32 s2, s2, 7
	s_lshl_b32 s80, s3, 6
	v_lshl_add_u32 v60, s74, 8, v119
	s_lshl_b32 s74, s74, 9
	s_or_b32 s2, s80, s2
	s_or_b32 s2, s2, s74
	v_add_u32_e32 v64, s2, v121
	v_readlane_b32 s2, v255, 18
	s_or_b32 s2, s2, s75
	s_or_b32 s2, s2, s78
	s_lshl_b32 s2, s2, 16
	s_lshl_b32 s3, s3, 17
	s_or_b32 s74, s3, s2
	s_lshl_b64 s[2:3], s[82:83], 7
	v_readlane_b32 s80, v253, 61
	v_readlane_b32 s81, v253, 62
	s_add_u32 s2, s80, s2
	v_mov_b32_e32 v5, v3
	s_waitcnt vmcnt(11)
	v_mul_f32_e32 v52, 0x3fb8aa3b, v52
	s_addc_u32 s3, s81, s3
	v_exp_f32_e32 v141, v52
	v_lshl_add_u64 v[52:53], s[86:87], 0, v[2:3]
	v_mul_f32_e32 v141, 0x3fb8aa3b, v141
	v_lshl_add_u64 v[4:5], s[2:3], 0, v[4:5]
	global_load_dwordx2 v[92:93], v[52:53], off
	global_load_dword v2, v[4:5], off
	s_lshl_b64 s[0:1], s[0:1], 14
	s_add_u32 s0, s0, s74
	v_mov_b32_e32 v55, v3
	v_mov_b32_e32 v57, v3
	v_mov_b32_e32 v59, v3
	v_mov_b32_e32 v61, v3
	v_mov_b32_e32 v63, v3
	v_mov_b32_e32 v65, v3
	v_lshl_add_u64 v[86:87], v[50:51], 0, s[22:23]
	s_addc_u32 s1, s1, 0
	v_mov_b32_e32 v50, 0
	v_lshl_add_u64 v[4:5], s[24:25], 0, v[54:55]
	v_lshl_add_u64 v[80:81], s[22:23], 0, v[58:59]
	v_lshl_add_u64 v[84:85], s[22:23], 0, v[62:63]
	v_lshl_add_u64 v[88:89], s[22:23], 0, v[64:65]
	v_lshl_add_u64 v[90:91], s[0:1], 0, v[74:75]
	s_add_u32 s2, s30, 0x9300000
	s_addc_u32 s3, s31, 0
	v_lshl_add_u64 v[78:79], v[88:89], 0, s[2:3]
	s_add_u32 s2, s30, 0x9480000
	s_addc_u32 s3, s31, 0
	v_lshl_add_u64 v[80:81], v[80:81], 0, s[2:3]
	v_lshl_add_u64 v[84:85], v[84:85], 0, s[2:3]
	v_lshl_add_u64 v[86:87], v[86:87], 0, s[2:3]
	v_lshl_add_u64 v[88:89], v[88:89], 0, s[2:3]
	s_add_u32 s2, s30, 0x15304000
	s_addc_u32 s3, s31, 0
	v_lshl_add_u64 v[4:5], v[4:5], 0, s[2:3]
	s_add_u32 s2, s30, 0x15500000
	s_addc_u32 s3, s31, 0
	v_lshl_add_u64 v[90:91], v[90:91], 0, s[2:3]
	s_mov_b32 s2, 0
	v_mov_b32_e32 v51, v50
	v_mov_b32_e32 v52, v50
	v_mov_b32_e32 v53, v50
	v_mov_b32_e32 v54, v50
	v_mov_b32_e32 v55, v50
	v_mov_b32_e32 v56, v50
	v_mov_b32_e32 v57, v50
	v_mov_b32_e32 v58, v50
	v_mov_b32_e32 v59, v50
	v_mov_b32_e32 v61, v50
	v_mov_b32_e32 v60, v50
	v_mov_b32_e32 v62, v50
	v_mov_b32_e32 v63, v50
	v_mov_b32_e32 v64, v50
	v_readlane_b32 s78, v254, 59
	s_branch .LBB0_720
.LBB0_719:
	s_or_b64 exec, exec, s[0:1]
	s_mov_b64 s[0:1], 0x200
	s_add_i32 s2, s2, 2
	v_lshl_add_u64 v[90:91], v[90:91], 0, s[0:1]
	s_and_b64 vcc, exec, s[86:87]
	v_mov_b64_e32 v[96:97], v[94:95]
	s_waitcnt vmcnt(2)
	v_mov_b64_e32 v[92:93], v[98:99]
	v_mov_b32_e32 v58, v51
	s_waitcnt lgkmcnt(0)
	v_mov_b32_e32 v59, v52
	v_mov_b32_e32 v61, v53
	v_mov_b32_e32 v60, v54
	v_mov_b32_e32 v62, v55
	v_mov_b32_e32 v63, v56
	v_mov_b32_e32 v64, v57
	s_cbranch_vccnz .LBB0_709
.LBB0_720:
	s_waitcnt vmcnt(6)
	v_mul_f32_e64 v65, v140, -v141
	v_mov_b32_e32 v66, 0
	v_add_u32_e32 v142, s36, v110
	v_mov_b32_dpp v65, v65 row_shr:1 row_mask:0xf bank_mask:0xf bound_ctrl:1
	v_fma_f32 v65, v140, -v141, v65
	s_and_b64 vcc, exec, s[20:21]
	s_nop 0
	v_add_f32_dpp v65, v65, v65 row_shr:2 row_mask:0xf bank_mask:0xf bound_ctrl:1
	s_nop 1
	v_add_f32_dpp v65, v65, v65 row_shr:4 row_mask:0xf bank_mask:0xf bound_ctrl:1
	s_nop 1
	v_add_f32_dpp v65, v65, v65 row_shr:8 row_mask:0xf bank_mask:0xf bound_ctrl:1
	s_nop 1
	v_mov_b32_dpp v66, v65 row_bcast:15 row_mask:0xa bank_mask:0xf
	v_add_f32_e32 v65, v65, v66
	v_mov_b32_e32 v66, 0
	s_nop 1
	v_mov_b32_dpp v66, v65 row_bcast:31 row_mask:0xc bank_mask:0xf
	v_add_f32_e32 v65, v65, v66
	ds_write2st64_b32 v126, v65, v140 offset1:1
	v_readlane_b32 s3, v65, 63
	v_cvt_pk_bf16_f32 v58, v50, v58
	v_cvt_pk_bf16_f32 v59, v59, v61
	ds_write_b64 v122, v[58:59]
	v_cvt_pk_bf16_f32 v58, v60, v62
	v_cvt_pk_bf16_f32 v59, v63, v64
	s_nop 0
	v_sub_f32_e32 v66, s3, v65
	v_exp_f32_e32 v66, v66
	ds_write_b64 v122, v[58:59] offset:4352
	v_lshlrev_b32_e32 v58, 16, v10
	v_and_b32_e32 v59, 0xffff0000, v10
	v_mul_f32_e32 v62, v140, v66
	ds_bpermute_b32 v82, v189, v62
	ds_bpermute_b32 v192, v190, v62
	v_lshlrev_b32_e32 v60, 16, v11
	v_and_b32_e32 v61, 0xffff0000, v11
	ds_write_b128 v127, v[14:17]
	ds_write_b128 v127, v[10:13] offset:17408
	v_lshlrev_b32_e32 v64, 16, v12
	v_and_b32_e32 v65, 0xffff0000, v12
	v_lshlrev_b32_e32 v66, 16, v13
	v_and_b32_e32 v67, 0xffff0000, v13
	s_waitcnt lgkmcnt(2)
	v_pk_mul_f32 v[58:59], v[58:59], v[82:83] op_sel_hi:[1,0]
	v_pk_mul_f32 v[60:61], v[60:61], v[82:83] op_sel_hi:[1,0]
	v_pk_mul_f32 v[64:65], v[64:65], v[82:83] op_sel_hi:[1,0]
	v_pk_mul_f32 v[66:67], v[66:67], v[82:83] op_sel_hi:[1,0]
	v_cvt_pk_bf16_f32 v58, v58, v59
	v_cvt_pk_bf16_f32 v59, v60, v61
	v_cvt_pk_bf16_f32 v60, v64, v65
	v_cvt_pk_bf16_f32 v61, v66, v67
	ds_write_b128 v188, v[58:61] offset:34816
	ds_write_b128 v129, v[22:25]
	ds_write_b128 v129, v[18:21] offset:17408
	v_lshlrev_b32_e32 v58, 16, v18
	v_and_b32_e32 v59, 0xffff0000, v18
	v_lshlrev_b32_e32 v60, 16, v19
	v_and_b32_e32 v61, 0xffff0000, v19
	v_lshlrev_b32_e32 v64, 16, v20
	v_and_b32_e32 v65, 0xffff0000, v20
	v_lshlrev_b32_e32 v66, 16, v21
	v_and_b32_e32 v67, 0xffff0000, v21
	v_pk_mul_f32 v[58:59], v[58:59], v[192:193] op_sel_hi:[1,0]
	v_pk_mul_f32 v[60:61], v[60:61], v[192:193] op_sel_hi:[1,0]
	v_pk_mul_f32 v[64:65], v[64:65], v[192:193] op_sel_hi:[1,0]
	v_pk_mul_f32 v[66:67], v[66:67], v[192:193] op_sel_hi:[1,0]
	v_cvt_pk_bf16_f32 v58, v58, v59
	v_cvt_pk_bf16_f32 v59, v60, v61
	v_cvt_pk_bf16_f32 v60, v64, v65
	v_cvt_pk_bf16_f32 v61, v66, v67
	ds_write_b128 v188, v[58:61] offset:44032
	s_cbranch_vccnz .LBB0_722
	ds_write_b128 v130, v[26:29] offset:53248
.LBB0_722:
	s_cmp_lt_u32 s2, 62
	s_cselect_b64 s[82:83], -1, 0
	s_cmp_gt_u32 s2, 61
	s_cselect_b64 s[86:87], -1, 0
	s_and_b64 vcc, exec, s[86:87]
	s_waitcnt lgkmcnt(0)
	s_barrier
	s_cbranch_vccnz .LBB0_726
	global_load_dwordx4 v[10:13], v[80:81], off offset:-2048
	global_load_dwordx4 v[14:17], v[80:81], off
	global_load_dwordx4 v[18:21], v[84:85], off offset:-2048
	global_load_dwordx4 v[22:25], v[84:85], off
	s_mov_b64 s[0:1], 0xc0000
	v_lshl_add_u64 v[80:81], v[80:81], 0, s[0:1]
	v_lshl_add_u64 v[84:85], v[84:85], 0, s[0:1]
	s_and_b64 vcc, exec, s[20:21]
	s_cbranch_vccnz .LBB0_725
	global_load_dwordx4 v[26:29], v[86:87], off
	v_lshl_add_u64 v[86:87], v[86:87], 0, s[0:1]
.LBB0_725:
	global_load_dwordx2 v[94:95], v[88:89], off
	v_lshl_add_u64 v[88:89], v[88:89], 0, s[0:1]
	global_load_dword v140, v[4:5], off
	s_mov_b64 s[0:1], 0x2000
	v_lshl_add_u64 v[4:5], v[4:5], 0, s[0:1]
	s_branch .LBB0_727

; #define LAS __attribute__((address_space(3)))
; __device__ __forceinline__ unsigned pk2(float lo, float hi) { unsigned r; asm volatile("v_cvt_pk_bf16_f32 %0, %1, %2" : "=v"(r) : "v"(lo), "v"(hi)); return r; }
; template <bool DRY>
; __device__ __forceinline__ void ssd_chunk(SsdRegs& R, f32x4 (&st)[2], LAS unsigned char* L, bf16_t* BIG, const float* DT, float* SSQY, const SsdItem& I, int c, int tid, int lane, int wave, int li, int pi, int c16, int q4) {
;     ...
;     bf16x8 cfr[4];
; #pragma unroll
;     for (int kk = 0; kk < 4; ++kk) cfr[kk] = SSD_FRAG(CS, PC, 16 * li, kk);
;     {
;         const int l = 16 * li + c16; const float acs_l = *(const LAS float*)(SCW + l * 4);
; #pragma unroll
;         for (int t = 0; t < 2; ++t) {
;             const int si = 2 * pi + t;
;             u32x2 w; w.x = 0u; w.y = 0u;
;             if (si <= li) {
;                 f32x4 d = (f32x4){0.f, 0.f, 0.f, 0.f};
; #pragma unroll
;                 for (int kk = 0; kk < 4; ++kk) d = __builtin_amdgcn_mfma_f32_16x16x32_bf16(SSD_FRAG(BS, PC, 16 * si, kk), cfr[kk], d, 0, 0, 0);
;                 float gv[4];
;                 const f32x4 acs_s = *(const LAS f32x4*)(SCW + (16 * si + 4 * q4) * 4), dt_s = *(const LAS f32x4*)(SCW + 256 + (16 * si + 4 * q4) * 4);
; #pragma unroll
;                 for (int e = 0; e < 4; ++e) gv[e] = d[e] * __expf(acs_l - acs_s[e]) * dt_s[e];
;                 if (si == li) {
; #pragma unroll
;                     for (int e = 0; e < 4; ++e) gv[e] = (4 * q4 + e <= c16) ? gv[e] : 0.f;
;                 }
;                 w.x = pk2(gv[0], gv[1]); w.y = pk2(gv[2], gv[3]);
;             }
.LBB0_727:
	ds_read_b128 v[70:73], v131
	ds_read_b128 v[66:69], v131 offset:64
	ds_read_b128 v[62:65], v131 offset:128
	ds_read_b128 v[58:61], v131 offset:192
	ds_read_b32 v76, v132
	v_mov_b32_e32 v106, 0
	v_cndmask_b32_e64 v107, 0, 1, s[88:89]
	v_cmp_ne_u32_e64 s[22:23], 1, v107
	s_andn2_b64 vcc, exec, s[88:89]
	v_mov_b32_e32 v107, v106
	s_cbranch_vccnz .LBB0_729
	ds_read_b128 v[144:147], v133 offset:17408
	ds_read_b128 v[148:151], v133 offset:17472
	ds_read_b128 v[176:179], v133 offset:17536
	ds_read_b128 v[180:183], v133 offset:17600
	ds_read_b128 v[184:187], v134
	ds_read_b128 v[152:155], v134 offset:256
	s_waitcnt lgkmcnt(5)
	v_mfma_f32_16x16x32_bf16 v[144:147], v[144:147], v[70:73], 0
	s_waitcnt lgkmcnt(4)
	v_mfma_f32_16x16x32_bf16 v[144:147], v[148:151], v[66:69], v[144:147]
	s_waitcnt lgkmcnt(3)
	v_mfma_f32_16x16x32_bf16 v[144:147], v[176:179], v[62:65], v[144:147]
	s_waitcnt lgkmcnt(2)
	v_mfma_f32_16x16x32_bf16 v[144:147], v[180:183], v[58:61], v[144:147]
	s_waitcnt lgkmcnt(1)
	v_sub_f32_e32 v106, v76, v184
	v_sub_f32_e32 v107, v76, v185
	v_exp_f32_e32 v106, v106
	v_exp_f32_e32 v107, v107
	v_sub_f32_e32 v143, v76, v186
	v_pk_mul_f32 v[106:107], v[144:145], v[106:107]
	v_exp_f32_e32 v144, v143
	v_sub_f32_e32 v143, v76, v187
	v_exp_f32_e32 v145, v143
	s_waitcnt lgkmcnt(0)
	v_pk_mul_f32 v[106:107], v[152:153], v[106:107]
	v_pk_mul_f32 v[144:145], v[146:147], v[144:145]
	s_nop 0
	v_pk_mul_f32 v[144:145], v[154:155], v[144:145]
	v_cndmask_b32_e64 v143, v106, 0, s[6:7]
	v_cndmask_b32_e64 v146, 0, v107, s[8:9]
	v_cndmask_b32_e64 v147, v144, 0, s[10:11]
	v_cndmask_b32_e64 v148, v145, 0, s[12:13]
	v_cndmask_b32_e64 v106, v106, v143, s[4:5]
	v_cndmask_b32_e64 v107, v107, v146, s[4:5]
	v_cndmask_b32_e64 v144, v144, v147, s[4:5]
	v_cndmask_b32_e64 v145, v145, v148, s[4:5]
	v_cvt_pk_bf16_f32 v106, v106, v107
	v_cvt_pk_bf16_f32 v107, v144, v145

; template <bool DRY>
; __device__ __forceinline__ void ssd_chunk(SsdRegs& R, f32x4 (&st)[2], LAS unsigned char* L, bf16_t* BIG, const float* DT, float* SSQY, const SsdItem& I, int c, int tid, int lane, int wave, int li, int pi, int c16, int q4) {
;     ...
;             if (si <= li) {
;                 f32x4 d = (f32x4){0.f, 0.f, 0.f, 0.f};
; #pragma unroll
;                 for (int kk = 0; kk < 4; ++kk) d = __builtin_amdgcn_mfma_f32_16x16x32_bf16(SSD_FRAG(BS, PC, 16 * si, kk), cfr[kk], d, 0, 0, 0);
;                 float gv[4];
;                 const f32x4 acs_s = *(const LAS f32x4*)(SCW + (16 * si + 4 * q4) * 4), dt_s = *(const LAS f32x4*)(SCW + 256 + (16 * si + 4 * q4) * 4);
; #pragma unroll
;                 for (int e = 0; e < 4; ++e) gv[e] = d[e] * __expf(acs_l - acs_s[e]) * dt_s[e];
;                 if (si == li) {
; #pragma unroll
;                     for (int e = 0; e < 4; ++e) gv[e] = (4 * q4 + e <= c16) ? gv[e] : 0.f;
;                 }
;                 w.x = pk2(gv[0], gv[1]); w.y = pk2(gv[2], gv[3]);
;             }
;             *(LAS u32x2*)(L + GG + l * PT + (16 * si + 4 * q4) * 2) = w;
;         }
;     }
;     f32x4 stn[2];
;     bf16x8 xfr[2][2], bwf[2];
; #pragma unroll
;     for (int kk = 0; kk < 2; ++kk) { bwf[kk] = SSD_TR(BW, PB, trB, wave, kk); xfr[0][kk] = SSD_TR(XI, PX, trX, 0, kk); xfr[1][kk] = SSD_TR(XI, PX, trX, 1, kk); }
; #pragma unroll
;     for (int pt = 0; pt < 2; ++pt) {
;         f32x4 d = st[pt] * etot;
; #pragma unroll
;         for (int kk = 0; kk < 2; ++kk) d = __builtin_amdgcn_mfma_f32_16x16x32_bf16(bwf[kk], xfr[pt][kk], d, 0, 0, 0);
;         stn[pt] = d;
;     }
;     const bf16x8 xy0 = pi ? xfr[1][0] : xfr[0][0], xy1 = pi ? xfr[1][1] : xfr[0][1];
;     st[0] = stn[0]; st[1] = stn[1];
;     __syncthreads();
;     {
;         f32x4 d1 = (f32x4){0.f, 0.f, 0.f, 0.f}, d2 = (f32x4){0.f, 0.f, 0.f, 0.f};
; #pragma unroll
;         for (int kk = 0; kk < 2; ++kk) d1 = __builtin_amdgcn_mfma_f32_16x16x32_bf16(kk ? xy1 : xy0, SSD_FRAG(GG, PT, 16 * li, kk), d1, 0, 0, 0);
; #pragma unroll
;         for (int kk = 0; kk < 4; ++kk) d2 = __builtin_amdgcn_mfma_f32_16x16x32_bf16(SSD_FRAG(SB, PC, 16 * pi, kk), cfr[kk], d2, 0, 0, 0);
;         const int l = 16 * li + c16; const float ea_l = __expf(*(const LAS float*)(SCW + l * 4));
;         const float zf[4] = {bf_lo(zc.x), bf_hi(zc.x), bf_lo(zc.y), bf_hi(zc.y)};
.LBB0_731:
	v_mov_b32_e32 v106, 0
	s_andn2_b64 vcc, exec, s[0:1]
	v_mov_b32_e32 v107, 0
	s_cbranch_vccnz .LBB0_733
	ds_read_b128 v[146:149], v135 offset:17408
	ds_read_b128 v[150:153], v135 offset:17472
	ds_read_b128 v[176:179], v135 offset:17536
	ds_read_b128 v[180:183], v135 offset:17600
	ds_read_b128 v[184:187], v136
	ds_read_b128 v[154:157], v136 offset:256
	s_waitcnt lgkmcnt(5)
	v_mfma_f32_16x16x32_bf16 v[146:149], v[146:149], v[70:73], 0
	s_waitcnt lgkmcnt(4)
	v_mfma_f32_16x16x32_bf16 v[146:149], v[150:153], v[66:69], v[146:149]
	s_waitcnt lgkmcnt(3)
	v_mfma_f32_16x16x32_bf16 v[146:149], v[176:179], v[62:65], v[146:149]
	s_waitcnt lgkmcnt(2)
	v_mfma_f32_16x16x32_bf16 v[146:149], v[180:183], v[58:61], v[146:149]
	s_waitcnt lgkmcnt(1)
	v_sub_f32_e32 v106, v76, v184
	v_sub_f32_e32 v107, v76, v185
	v_exp_f32_e32 v106, v106
	v_exp_f32_e32 v107, v107
	v_sub_f32_e32 v143, v76, v186
	v_sub_f32_e32 v76, v76, v187
	v_pk_mul_f32 v[106:107], v[146:147], v[106:107]
	v_exp_f32_e32 v146, v143
	v_exp_f32_e32 v147, v76
	s_waitcnt lgkmcnt(0)
	v_pk_mul_f32 v[106:107], v[154:155], v[106:107]
	v_pk_mul_f32 v[146:147], v[148:149], v[146:147]
	s_nop 0
	v_pk_mul_f32 v[146:147], v[156:157], v[146:147]
	v_cndmask_b32_e64 v76, v106, 0, s[6:7]
	v_cndmask_b32_e64 v143, 0, v107, s[8:9]
	v_cndmask_b32_e64 v145, v146, 0, s[10:11]
	v_cndmask_b32_e64 v148, v147, 0, s[12:13]
	v_cndmask_b32_e64 v76, v106, v76, s[14:15]
	v_cndmask_b32_e64 v106, v107, v143, s[14:15]
	v_cndmask_b32_e64 v145, v146, v145, s[14:15]
	v_cndmask_b32_e64 v146, v147, v148, s[14:15]
	v_cvt_pk_bf16_f32 v106, v76, v106
	v_cvt_pk_bf16_f32 v107, v145, v146
.LBB0_733:
	v_add_u32_e32 v145, s69, v113
	s_waitcnt lgkmcnt(1)
	ds_write_b64 v145, v[106:107]
	ds_read_b64_tr_b16 v[146:147], v137 offset:34816
	ds_read_b64_tr_b16 v[148:149], v137 offset:35968
	v_exp_f32_e32 v76, s3
	ds_read_b64_tr_b16 v[152:153], v138 offset:53632
	ds_read_b64_tr_b16 v[150:151], v138 offset:53248
	ds_read_b64_tr_b16 v[154:155], v137 offset:44032
	ds_read_b64_tr_b16 v[156:157], v137 offset:45184
	ds_read_b64_tr_b16 v[158:159], v138 offset:56320
	ds_read_b64_tr_b16 v[160:161], v138 offset:56704
	ds_read_b64_tr_b16 v[162:163], v138 offset:53280
	ds_read_b64_tr_b16 v[164:165], v138 offset:53664
	ds_read_b64_tr_b16 v[166:167], v138 offset:56352
	ds_read_b64_tr_b16 v[168:169], v138 offset:56736
	v_pk_mul_f32 v[52:53], v[52:53], v[76:77] op_sel_hi:[1,0]
	v_pk_mul_f32 v[50:51], v[50:51], v[76:77] op_sel_hi:[1,0]
	v_pk_mul_f32 v[56:57], v[56:57], v[76:77] op_sel_hi:[1,0]
	v_pk_mul_f32 v[54:55], v[54:55], v[76:77] op_sel_hi:[1,0]
	s_waitcnt lgkmcnt(8)
	v_mfma_f32_16x16x32_bf16 v[50:53], v[146:149], v[150:153], v[50:53]
	v_add_u32_e32 v143, v112, v111
	s_waitcnt lgkmcnt(0)
	s_barrier
	v_mfma_f32_16x16x32_bf16 v[54:57], v[146:149], v[162:165], v[54:57]
	v_cndmask_b32_e64 v149, v165, v153, s[16:17]
	v_cndmask_b32_e64 v148, v164, v152, s[16:17]
	v_cndmask_b32_e64 v147, v163, v151, s[16:17]
	v_cndmask_b32_e64 v146, v162, v150, s[16:17]
	v_mfma_f32_16x16x32_bf16 v[50:53], v[154:157], v[158:161], v[50:53]
	v_cmp_lt_i32_e32 vcc, v213, v208
	v_cmp_lt_i32_e64 s[0:1], v214, v208
	v_mfma_f32_16x16x32_bf16 v[54:57], v[154:157], v[166:169], v[54:57]
	ds_read_b128 v[150:153], v143
	ds_read_b128 v[154:157], v123
	ds_read_b32 v76, v132
	s_waitcnt lgkmcnt(2)
	v_mfma_f32_16x16x32_bf16 v[146:149], v[146:149], v[150:153], 0
	ds_read_b128 v[150:153], v123 offset:64
	s_waitcnt lgkmcnt(2)
	v_mfma_f32_16x16x32_bf16 v[70:73], v[154:157], v[70:73], 0
	ds_read_b128 v[154:157], v123 offset:128
	s_waitcnt lgkmcnt(1)
	v_mfma_f32_16x16x32_bf16 v[66:69], v[150:153], v[66:69], v[70:73]
	v_cndmask_b32_e64 v153, v169, v161, s[16:17]
	s_nop 3
	ds_read_b128 v[70:73], v123 offset:192
	v_cndmask_b32_e64 v152, v168, v160, s[16:17]
	s_waitcnt lgkmcnt(1)
	v_mfma_f32_16x16x32_bf16 v[62:65], v[154:157], v[62:65], v[66:69]
	v_cndmask_b32_e64 v151, v167, v159, s[16:17]
	v_cndmask_b32_e64 v150, v166, v158, s[16:17]
	s_nop 0
	ds_read_b128 v[66:69], v143 offset:64
	s_waitcnt lgkmcnt(1)
	v_mfma_f32_16x16x32_bf16 v[58:61], v[70:73], v[58:61], v[62:65]
	v_lshlrev_b32_e32 v70, 16, v96
	s_nop 1
	v_exp_f32_e32 v72, v76
	v_mul_f32_e32 v62, 0xbfb8aa3b, v70
	v_exp_f32_e32 v71, v62
	s_waitcnt lgkmcnt(0)
	v_mfma_f32_16x16x32_bf16 v[62:65], v[150:153], v[66:69], v[146:149]
	ds_read_b64 v[66:67], v139 offset:53248
	s_nop 6
	v_fma_f32 v62, v58, v72, v62
	v_add_f32_e32 v58, 1.0, v71
	v_rcp_f32_e32 v76, v58
	v_and_b32_e32 v58, 0xffff0000, v96
	v_mul_f32_e32 v68, 0xbfb8aa3b, v58
	v_exp_f32_e32 v73, v68
	s_waitcnt lgkmcnt(0)
	v_lshlrev_b32_e32 v71, 16, v66
	v_pk_mul_f32 v[68:69], v[76:77], v[70:71]
	v_fma_f32 v63, v59, v72, v63
	v_add_f32_e32 v62, v62, v69
	v_add_f32_e32 v69, 1.0, v73
	v_rcp_f32_e32 v76, v69
	v_and_b32_e32 v59, 0xffff0000, v66
	v_mul_f32_e32 v62, v68, v62
	v_fma_f32 v64, v60, v72, v64
	v_pk_mul_f32 v[58:59], v[76:77], v[58:59]
	v_fmac_f32_e32 v65, v61, v72
	v_add_f32_e32 v59, v63, v59
	v_mul_f32_e32 v63, v58, v59
	v_lshlrev_b32_e32 v58, 16, v97
	v_mul_f32_e32 v59, 0xbfb8aa3b, v58
	v_exp_f32_e32 v68, v59
	v_lshlrev_b32_e32 v59, 16, v67
	v_and_b32_e32 v61, 0xffff0000, v67
	v_mul_f32_e32 v66, v63, v63
	v_add_f32_e32 v60, 1.0, v68
	v_rcp_f32_e32 v76, v60
	v_and_b32_e32 v60, 0xffff0000, v97
	v_mul_f32_e32 v68, 0xbfb8aa3b, v60
	v_exp_f32_e32 v68, v68
	v_pk_mul_f32 v[58:59], v[76:77], v[58:59]
	v_fmac_f32_e32 v66, v62, v62
	v_add_f32_e32 v59, v64, v59
	v_mul_f32_e32 v64, v58, v59
	v_add_f32_e32 v58, 1.0, v68
	v_rcp_f32_e32 v76, v58
	v_fmac_f32_e32 v66, v64, v64
	v_pk_mul_f32 v[58:59], v[76:77], v[60:61]
	s_nop 0
	v_add_f32_e32 v59, v65, v59
	v_mul_f32_e32 v58, v58, v59
	v_cndmask_b32_e32 v59, v207, v213, vcc
	v_fmac_f32_e32 v66, v58, v58
	v_lshlrev_b32_e32 v146, 2, v59
	ds_bpermute_b32 v59, v146, v66
	v_cvt_pk_bf16_f32 v60, v62, v63
	v_cvt_pk_bf16_f32 v61, v64, v58
	s_waitcnt lgkmcnt(0)
	v_add_f32_e32 v58, v66, v59
	v_cndmask_b32_e64 v59, v207, v214, s[0:1]
	v_lshlrev_b32_e32 v147, 2, v59
	ds_bpermute_b32 v59, v147, v58
	global_store_dwordx2 v[78:79], v[60:61], off
	s_mov_b64 s[0:1], 0xc0000
	v_lshl_add_u64 v[78:79], v[78:79], 0, s[0:1]
	s_and_saveexec_b64 s[0:1], s[18:19]
	s_cbranch_execz .LBB0_735
	s_waitcnt lgkmcnt(0)
	v_add_f32_e32 v60, v58, v59
	global_store_dword v[90:91], v60, off
; #define LAS __attribute__((address_space(3)))
; __device__ __forceinline__ void ssd_load(SsdRegs& R, const bf16_t* BIG, const float* DT, const SsdItem& I, int cc, int wave) {
;     const size_t r0 = (size_t)I.b * SEQ_ + (size_t)cc * 64;
;     const char* cb = (const char*)BIG + r0 * (BIGW * 2); const char* cd = (const char*)DT + r0 * 128;
; #pragma unroll
; template <bool DRY>
; __device__ __forceinline__ void ssd_chunk(SsdRegs& R, f32x4 (&st)[2], LAS unsigned char* L, bf16_t* BIG, const float* DT, float* SSQY, const SsdItem& I, int c, int tid, int lane, int wave, int li, int pi, int c16, int q4) {
;     ...
;     const float dtl = R.rdt;
;     float acs = dtl * I.Ah;
;     acs += dppz<0x111>(acs); acs += dppz<0x112>(acs); acs += dppz<0x114>(acs); acs += dppz<0x118>(acs);
;     acs += __builtin_bit_cast(float, __builtin_amdgcn_update_dpp(0, __builtin_bit_cast(int, acs), 0x142, 0xa, 0xf, false));
;     acs += __builtin_bit_cast(float, __builtin_amdgcn_update_dpp(0, __builtin_bit_cast(int, acs), 0x143, 0xc, 0xf, false));
;     const float tot = __builtin_bit_cast(float, __builtin_amdgcn_readlane(__builtin_bit_cast(int, acs), 63));
;     const float wl = dtl * __expf(tot - acs), etot = __expf(tot);
;     LAS unsigned char* SCW = L + SCT + wave * 512;
;     *(LAS float*)(SCW + lane * 4) = acs; *(LAS float*)(SCW + 256 + lane * 4) = dtl;
; #pragma unroll
;     for (int pt = 0; pt < 2; ++pt) { u32x2 w; w.x = pk2(st[pt][0], st[pt][1]); w.y = pk2(st[pt][2], st[pt][3]); *(LAS u32x2*)(L + SB + (16 * pt + c16) * PC + (16 * wave + 4 * q4) * 2) = w; }
; #pragma unroll
;     for (int i = 0; i < 2; ++i) {
;         const int id = tid + 512 * i; *(LAS u32x4*)(L + CS + (id >> 4) * PC + (id & 15) * 16) = (u32x4){R.rc[i].x, R.rc[i].y, R.rc[i].z, R.rc[i].w};
;         const int n8 = wave + 8 * i; *(LAS u32x4*)(L + BS + lane * PC + n8 * 16) = (u32x4){R.rb[i].x, R.rb[i].y, R.rb[i].z, R.rb[i].w};
;         float f[8]; unpack8(R.rb[i], f);
;         u32x4 bwv; bwv.x = pk2(f[0] * wl, f[1] * wl); bwv.y = pk2(f[2] * wl, f[3] * wl); bwv.z = pk2(f[4] * wl, f[5] * wl); bwv.w = pk2(f[6] * wl, f[7] * wl);
;         *(LAS u32x4*)(L + BW + lane * PB + n8 * 16) = bwv;
;     }
;     if (wave < 4) *(LAS u32x4*)(L + XI + lane * PX + wave * 16) = (u32x4){R.rx.x, R.rx.y, R.rx.z, R.rx.w};
;     const u32x2 zc = R.rz;
;     __syncthreads();
;     if (c + 2 < 64) ssd_load(R, BIG, DT, I, c + 2, wave);
.LBB0_735:
	s_or_b64 exec, exec, s[0:1]
	s_waitcnt vmcnt(1)
	v_mul_f32_e64 v58, v2, -v141
	s_waitcnt lgkmcnt(0)
	v_mov_b32_e32 v59, 0
	v_and_b32_e32 v61, 0xffff0000, v31
	v_mov_b32_dpp v58, v58 row_shr:1 row_mask:0xf bank_mask:0xf bound_ctrl:1
	v_fma_f32 v58, v2, -v141, v58
	v_lshlrev_b32_e32 v64, 16, v32
	v_and_b32_e32 v65, 0xffff0000, v32
	v_add_f32_dpp v58, v58, v58 row_shr:2 row_mask:0xf bank_mask:0xf bound_ctrl:1
	v_lshlrev_b32_e32 v66, 16, v33
	v_and_b32_e32 v67, 0xffff0000, v33
	v_add_f32_dpp v58, v58, v58 row_shr:4 row_mask:0xf bank_mask:0xf bound_ctrl:1
	s_and_b64 vcc, exec, s[20:21]
	s_nop 0
	v_add_f32_dpp v58, v58, v58 row_shr:8 row_mask:0xf bank_mask:0xf bound_ctrl:1
	s_nop 1
	v_mov_b32_dpp v59, v58 row_bcast:15 row_mask:0xa bank_mask:0xf
	v_add_f32_e32 v58, v58, v59
	v_mov_b32_e32 v59, 0
	s_nop 1
	v_mov_b32_dpp v59, v58 row_bcast:31 row_mask:0xc bank_mask:0xf
	v_add_f32_e32 v58, v58, v59
	ds_write2st64_b32 v126, v58, v2 offset1:1
	v_readlane_b32 s3, v58, 63
	s_nop 1
	v_sub_f32_e32 v59, s3, v58
	v_exp_f32_e32 v60, v59
	v_cvt_pk_bf16_f32 v58, v50, v51
	v_cvt_pk_bf16_f32 v59, v52, v53
	ds_write_b64 v124, v[58:59]
	v_cvt_pk_bf16_f32 v58, v54, v55
	v_cvt_pk_bf16_f32 v59, v56, v57
	ds_write_b64 v124, v[58:59] offset:4352
	v_mul_f32_e32 v62, v2, v60
	ds_bpermute_b32 v82, v189, v62
	ds_bpermute_b32 v192, v190, v62
	v_lshlrev_b32_e32 v58, 16, v30
	v_and_b32_e32 v59, 0xffff0000, v30
	v_lshlrev_b32_e32 v60, 16, v31
	ds_write_b128 v127, v[34:37]
	ds_write_b128 v127, v[30:33] offset:17408
	s_waitcnt lgkmcnt(2)
	v_pk_mul_f32 v[58:59], v[58:59], v[82:83] op_sel_hi:[1,0]
	v_pk_mul_f32 v[60:61], v[60:61], v[82:83] op_sel_hi:[1,0]
	v_pk_mul_f32 v[64:65], v[64:65], v[82:83] op_sel_hi:[1,0]
	v_pk_mul_f32 v[66:67], v[66:67], v[82:83] op_sel_hi:[1,0]
	v_cvt_pk_bf16_f32 v58, v58, v59
	v_cvt_pk_bf16_f32 v59, v60, v61
	v_cvt_pk_bf16_f32 v60, v64, v65
	v_cvt_pk_bf16_f32 v61, v66, v67
	ds_write_b128 v188, v[58:61] offset:34816
	ds_write_b128 v129, v[46:49]
	ds_write_b128 v129, v[42:45] offset:17408
	v_lshlrev_b32_e32 v58, 16, v42
	v_and_b32_e32 v59, 0xffff0000, v42
	v_lshlrev_b32_e32 v60, 16, v43
	v_and_b32_e32 v61, 0xffff0000, v43
	v_lshlrev_b32_e32 v64, 16, v44
	v_and_b32_e32 v65, 0xffff0000, v44
	v_lshlrev_b32_e32 v66, 16, v45
	v_and_b32_e32 v67, 0xffff0000, v45
	v_pk_mul_f32 v[58:59], v[58:59], v[192:193] op_sel_hi:[1,0]
	v_pk_mul_f32 v[60:61], v[60:61], v[192:193] op_sel_hi:[1,0]
	v_pk_mul_f32 v[64:65], v[64:65], v[192:193] op_sel_hi:[1,0]
	v_pk_mul_f32 v[66:67], v[66:67], v[192:193] op_sel_hi:[1,0]
	v_cvt_pk_bf16_f32 v58, v58, v59
	v_cvt_pk_bf16_f32 v59, v60, v61
	v_cvt_pk_bf16_f32 v60, v64, v65
	v_cvt_pk_bf16_f32 v61, v66, v67
	ds_write_b128 v188, v[58:61] offset:44032
	s_cbranch_vccnz .LBB0_737
	ds_write_b128 v130, v[38:41] offset:59392
.LBB0_737:
	s_andn2_b64 vcc, exec, s[82:83]
	s_waitcnt lgkmcnt(0)
	s_barrier
	s_cbranch_vccnz .LBB0_741
	global_load_dwordx4 v[30:33], v[80:81], off offset:-2048
	global_load_dwordx4 v[34:37], v[80:81], off
	global_load_dwordx4 v[42:45], v[84:85], off offset:-2048
	global_load_dwordx4 v[46:49], v[84:85], off
	s_mov_b64 s[0:1], 0xc0000
	v_lshl_add_u64 v[80:81], v[80:81], 0, s[0:1]
	v_lshl_add_u64 v[84:85], v[84:85], 0, s[0:1]
	s_and_b64 vcc, exec, s[20:21]
	s_cbranch_vccnz .LBB0_740
	global_load_dwordx4 v[38:41], v[86:87], off
	v_lshl_add_u64 v[86:87], v[86:87], 0, s[0:1]
.LBB0_740:
	global_load_dwordx2 v[98:99], v[88:89], off
	v_lshl_add_u64 v[88:89], v[88:89], 0, s[0:1]
	global_load_dword v2, v[4:5], off
	s_mov_b64 s[0:1], 0x2000
	v_lshl_add_u64 v[4:5], v[4:5], 0, s[0:1]
	s_branch .LBB0_742

; #define LAS __attribute__((address_space(3)))
; __device__ __forceinline__ unsigned pk2(float lo, float hi) { unsigned r; asm volatile("v_cvt_pk_bf16_f32 %0, %1, %2" : "=v"(r) : "v"(lo), "v"(hi)); return r; }
; template <bool DRY>
; __device__ __forceinline__ void ssd_chunk(SsdRegs& R, f32x4 (&st)[2], LAS unsigned char* L, bf16_t* BIG, const float* DT, float* SSQY, const SsdItem& I, int c, int tid, int lane, int wave, int li, int pi, int c16, int q4) {
;     ...
;     bf16x8 cfr[4];
; #pragma unroll
;     for (int kk = 0; kk < 4; ++kk) cfr[kk] = SSD_FRAG(CS, PC, 16 * li, kk);
;     {
;         const int l = 16 * li + c16; const float acs_l = *(const LAS float*)(SCW + l * 4);
; #pragma unroll
;         for (int t = 0; t < 2; ++t) {
;             const int si = 2 * pi + t;
;             u32x2 w; w.x = 0u; w.y = 0u;
;             if (si <= li) {
;                 f32x4 d = (f32x4){0.f, 0.f, 0.f, 0.f};
; #pragma unroll
;                 for (int kk = 0; kk < 4; ++kk) d = __builtin_amdgcn_mfma_f32_16x16x32_bf16(SSD_FRAG(BS, PC, 16 * si, kk), cfr[kk], d, 0, 0, 0);
;                 float gv[4];
;                 const f32x4 acs_s = *(const LAS f32x4*)(SCW + (16 * si + 4 * q4) * 4), dt_s = *(const LAS f32x4*)(SCW + 256 + (16 * si + 4 * q4) * 4);
; #pragma unroll
;                 for (int e = 0; e < 4; ++e) gv[e] = d[e] * __expf(acs_l - acs_s[e]) * dt_s[e];
;                 if (si == li) {
; #pragma unroll
;                     for (int e = 0; e < 4; ++e) gv[e] = (4 * q4 + e <= c16) ? gv[e] : 0.f;
;                 }
;                 w.x = pk2(gv[0], gv[1]); w.y = pk2(gv[2], gv[3]);
;             }
;             *(LAS u32x2*)(L + GG + l * PT + (16 * si + 4 * q4) * 2) = w;
.LBB0_742:
	ds_read_b128 v[70:73], v131
	ds_read_b128 v[66:69], v131 offset:64
	ds_read_b128 v[62:65], v131 offset:128
	ds_read_b128 v[58:61], v131 offset:192
	ds_read_b32 v76, v132
	v_mov_b32_e32 v100, 0
	s_and_b64 vcc, exec, s[22:23]
	v_mov_b32_e32 v101, v100
	s_cbranch_vccnz .LBB0_748
	ds_read_b128 v[100:103], v133 offset:17408
	ds_read_b128 v[148:151], v133 offset:17472
	ds_read_b128 v[176:179], v133 offset:17536
	ds_read_b128 v[180:183], v133 offset:17600
	ds_read_b128 v[184:187], v134
	ds_read_b128 v[152:155], v134 offset:256
	s_waitcnt lgkmcnt(5)
	v_mfma_f32_16x16x32_bf16 v[100:103], v[100:103], v[70:73], 0
	s_waitcnt lgkmcnt(4)
	v_mfma_f32_16x16x32_bf16 v[100:103], v[148:151], v[66:69], v[100:103]
	s_waitcnt lgkmcnt(3)
	v_mfma_f32_16x16x32_bf16 v[100:103], v[176:179], v[62:65], v[100:103]
	s_waitcnt lgkmcnt(2)
	v_mfma_f32_16x16x32_bf16 v[100:103], v[180:183], v[58:61], v[100:103]
	s_nop 1
	s_waitcnt lgkmcnt(1)
	v_sub_f32_e32 v104, v76, v184
	v_sub_f32_e32 v105, v76, v185
	v_exp_f32_e32 v104, v104
	v_exp_f32_e32 v105, v105
	s_nop 0
	v_pk_mul_f32 v[100:101], v[100:101], v[104:105]
	v_sub_f32_e32 v104, v76, v186
	v_sub_f32_e32 v105, v76, v187
	v_exp_f32_e32 v104, v104
	v_exp_f32_e32 v105, v105
	s_waitcnt lgkmcnt(0)
	v_pk_mul_f32 v[100:101], v[152:153], v[100:101]
	v_pk_mul_f32 v[102:103], v[102:103], v[104:105]
	s_nop 0
	v_pk_mul_f32 v[102:103], v[154:155], v[102:103]
	v_cndmask_b32_e64 v104, v100, 0, s[6:7]
	v_cndmask_b32_e64 v105, 0, v101, s[8:9]
	v_cndmask_b32_e64 v142, v102, 0, s[10:11]
	v_cndmask_b32_e64 v148, v103, 0, s[12:13]
	v_cndmask_b32_e64 v100, v100, v104, s[4:5]
	v_cndmask_b32_e64 v101, v101, v105, s[4:5]
	v_cndmask_b32_e64 v102, v102, v142, s[4:5]
	v_cndmask_b32_e64 v103, v103, v148, s[4:5]
	v_cvt_pk_bf16_f32 v100, v100, v101
	v_cvt_pk_bf16_f32 v101, v102, v103
	s_and_b64 vcc, exec, s[24:25]
	s_mov_b64 s[0:1], -1
	ds_write_b64 v144, v[100:101]
	s_cbranch_vccz .LBB0_749

; #define LAS __attribute__((address_space(3)))
; template <bool DRY>
; __device__ __forceinline__ void ssd_chunk(SsdRegs& R, f32x4 (&st)[2], LAS unsigned char* L, bf16_t* BIG, const float* DT, float* SSQY, const SsdItem& I, int c, int tid, int lane, int wave, int li, int pi, int c16, int q4) {
;     ...
;         const int l = 16 * li + c16; const float acs_l = *(const LAS float*)(SCW + l * 4);
; #pragma unroll
;         for (int t = 0; t < 2; ++t) {
;             const int si = 2 * pi + t;
;             u32x2 w; w.x = 0u; w.y = 0u;
;             if (si <= li) {
;                 f32x4 d = (f32x4){0.f, 0.f, 0.f, 0.f};
; #pragma unroll
;                 for (int kk = 0; kk < 4; ++kk) d = __builtin_amdgcn_mfma_f32_16x16x32_bf16(SSD_FRAG(BS, PC, 16 * si, kk), cfr[kk], d, 0, 0, 0);
;                 float gv[4];
;                 const f32x4 acs_s = *(const LAS f32x4*)(SCW + (16 * si + 4 * q4) * 4), dt_s = *(const LAS f32x4*)(SCW + 256 + (16 * si + 4 * q4) * 4);
; #pragma unroll
;                 for (int e = 0; e < 4; ++e) gv[e] = d[e] * __expf(acs_l - acs_s[e]) * dt_s[e];
;                 if (si == li) {
; #pragma unroll
;                     for (int e = 0; e < 4; ++e) gv[e] = (4 * q4 + e <= c16) ? gv[e] : 0.f;
;                 }
;                 w.x = pk2(gv[0], gv[1]); w.y = pk2(gv[2], gv[3]);
;             }
;             *(LAS u32x2*)(L + GG + l * PT + (16 * si + 4 * q4) * 2) = w;
;         }
;     }
;     f32x4 stn[2];
;     bf16x8 xfr[2][2], bwf[2];
; #pragma unroll
;     for (int kk = 0; kk < 2; ++kk) { bwf[kk] = SSD_TR(BW, PB, trB, wave, kk); xfr[0][kk] = SSD_TR(XI, PX, trX, 0, kk); xfr[1][kk] = SSD_TR(XI, PX, trX, 1, kk); }
; #pragma unroll
;     for (int pt = 0; pt < 2; ++pt) {
;         f32x4 d = st[pt] * etot;
; #pragma unroll
;         for (int kk = 0; kk < 2; ++kk) d = __builtin_amdgcn_mfma_f32_16x16x32_bf16(bwf[kk], xfr[pt][kk], d, 0, 0, 0);
;         stn[pt] = d;
;     }
;     const bf16x8 xy0 = pi ? xfr[1][0] : xfr[0][0], xy1 = pi ? xfr[1][1] : xfr[0][1];
;     st[0] = stn[0]; st[1] = stn[1];
;     __syncthreads();
;     {
;         f32x4 d1 = (f32x4){0.f, 0.f, 0.f, 0.f}, d2 = (f32x4){0.f, 0.f, 0.f, 0.f};
; #pragma unroll
;         for (int kk = 0; kk < 2; ++kk) d1 = __builtin_amdgcn_mfma_f32_16x16x32_bf16(kk ? xy1 : xy0, SSD_FRAG(GG, PT, 16 * li, kk), d1, 0, 0, 0);
; #pragma unroll
.LBB0_745:
	ds_read_b128 v[100:103], v135 offset:17408
	ds_read_b128 v[148:151], v135 offset:17472
	ds_read_b128 v[176:179], v135 offset:17536
	ds_read_b128 v[180:183], v135 offset:17600
	ds_read_b128 v[184:187], v136
	ds_read_b128 v[152:155], v136 offset:256
	s_waitcnt lgkmcnt(5)
	v_mfma_f32_16x16x32_bf16 v[100:103], v[100:103], v[70:73], 0
	s_waitcnt lgkmcnt(4)
	v_mfma_f32_16x16x32_bf16 v[100:103], v[148:151], v[66:69], v[100:103]
	s_waitcnt lgkmcnt(3)
	v_mfma_f32_16x16x32_bf16 v[100:103], v[176:179], v[62:65], v[100:103]
	s_waitcnt lgkmcnt(2)
	v_mfma_f32_16x16x32_bf16 v[100:103], v[180:183], v[58:61], v[100:103]
	s_nop 1
	s_waitcnt lgkmcnt(1)
	v_sub_f32_e32 v104, v76, v184
	v_sub_f32_e32 v105, v76, v185
	v_exp_f32_e32 v104, v104
	v_exp_f32_e32 v105, v105
	s_nop 0
	v_pk_mul_f32 v[100:101], v[100:101], v[104:105]
	v_sub_f32_e32 v104, v76, v186
	v_sub_f32_e32 v76, v76, v187
	v_exp_f32_e32 v104, v104
	v_exp_f32_e32 v105, v76
	s_waitcnt lgkmcnt(0)
	v_pk_mul_f32 v[100:101], v[152:153], v[100:101]
	v_pk_mul_f32 v[102:103], v[102:103], v[104:105]
	s_nop 0
	v_pk_mul_f32 v[102:103], v[154:155], v[102:103]
	v_cndmask_b32_e64 v76, v100, 0, s[6:7]
	v_cndmask_b32_e64 v104, 0, v101, s[8:9]
	v_cndmask_b32_e64 v105, v102, 0, s[10:11]
	v_cndmask_b32_e64 v142, v103, 0, s[12:13]
	v_cndmask_b32_e64 v76, v100, v76, s[14:15]
	v_cndmask_b32_e64 v100, v101, v104, s[14:15]
	v_cndmask_b32_e64 v102, v102, v105, s[14:15]
	v_cndmask_b32_e64 v103, v103, v142, s[14:15]
	v_cvt_pk_bf16_f32 v100, v76, v100
	v_cvt_pk_bf16_f32 v101, v102, v103
.LBB0_746:
	s_waitcnt lgkmcnt(1)
	v_exp_f32_e32 v76, s3
	ds_write_b64 v145, v[100:101]
	ds_read_b64_tr_b16 v[100:101], v137 offset:34816
	ds_read_b64_tr_b16 v[102:103], v137 offset:35968
	ds_read_b64_tr_b16 v[150:151], v138 offset:59776
	ds_read_b64_tr_b16 v[148:149], v138 offset:59392
	ds_read_b64_tr_b16 v[152:153], v137 offset:44032
	ds_read_b64_tr_b16 v[154:155], v137 offset:45184
	ds_read_b64_tr_b16 v[156:157], v138 offset:62464
	ds_read_b64_tr_b16 v[158:159], v138 offset:62848
	ds_read_b64_tr_b16 v[162:163], v138 offset:59808
	ds_read_b64_tr_b16 v[160:161], v138 offset:59424
	ds_read_b64_tr_b16 v[166:167], v138 offset:62880
	v_pk_mul_f32 v[52:53], v[52:53], v[76:77] op_sel_hi:[1,0]
	v_pk_mul_f32 v[50:51], v[50:51], v[76:77] op_sel_hi:[1,0]
	ds_read_b64_tr_b16 v[164:165], v138 offset:62496
	v_pk_mul_f32 v[56:57], v[56:57], v[76:77] op_sel_hi:[1,0]
	v_pk_mul_f32 v[54:55], v[54:55], v[76:77] op_sel_hi:[1,0]
	s_waitcnt lgkmcnt(8)
	v_mfma_f32_16x16x32_bf16 v[50:53], v[100:103], v[148:151], v[50:53]
	s_waitcnt lgkmcnt(0)
	s_barrier
	v_mfma_f32_16x16x32_bf16 v[54:57], v[100:103], v[160:163], v[54:57]
	v_cndmask_b32_e64 v103, v163, v151, s[16:17]
	v_cndmask_b32_e64 v102, v162, v150, s[16:17]
	v_cndmask_b32_e64 v101, v161, v149, s[16:17]
	v_mfma_f32_16x16x32_bf16 v[50:53], v[152:155], v[156:159], v[50:53]
	v_cndmask_b32_e64 v100, v160, v148, s[16:17]
	ds_read_b128 v[148:151], v143
	v_mfma_f32_16x16x32_bf16 v[54:57], v[152:155], v[164:167], v[54:57]
	ds_read_b128 v[152:155], v125
	s_waitcnt lgkmcnt(1)
	v_mfma_f32_16x16x32_bf16 v[100:103], v[100:103], v[148:151], 0
	ds_read_b128 v[148:151], v125 offset:64
	s_waitcnt lgkmcnt(1)
	v_mfma_f32_16x16x32_bf16 v[70:73], v[152:155], v[70:73], 0
	ds_read_b128 v[152:155], v125 offset:128
	s_waitcnt lgkmcnt(1)
	v_mfma_f32_16x16x32_bf16 v[66:69], v[148:151], v[66:69], v[70:73]
	s_nop 4
	ds_read_b128 v[70:73], v125 offset:192
	ds_read_b32 v76, v132
	v_cndmask_b32_e64 v151, v167, v159, s[16:17]
	v_cndmask_b32_e64 v150, v166, v158, s[16:17]
	s_waitcnt lgkmcnt(2)
	v_mfma_f32_16x16x32_bf16 v[62:65], v[152:155], v[62:65], v[66:69]
	v_cndmask_b32_e64 v149, v165, v157, s[16:17]
	v_cndmask_b32_e64 v148, v164, v156, s[16:17]
	s_nop 0
	v_lshlrev_b32_e32 v68, 16, v92
	s_waitcnt lgkmcnt(1)
	v_mfma_f32_16x16x32_bf16 v[58:61], v[70:73], v[58:61], v[62:65]
	v_mul_f32_e32 v69, 0xbfb8aa3b, v68
	v_exp_f32_e32 v69, v69
	s_waitcnt lgkmcnt(0)
	v_exp_f32_e32 v70, v76
	ds_read_b128 v[62:65], v143 offset:64
	ds_read_b64 v[66:67], v139 offset:59392
	s_waitcnt lgkmcnt(1)
	v_mfma_f32_16x16x32_bf16 v[62:65], v[148:151], v[62:65], v[100:103]
	s_nop 7
	v_fma_f32 v62, v58, v70, v62
	v_add_f32_e32 v58, 1.0, v69
	v_rcp_f32_e32 v76, v58
	v_and_b32_e32 v58, 0xffff0000, v92
	v_mul_f32_e32 v69, 0xbfb8aa3b, v58
	v_exp_f32_e32 v71, v69
	s_waitcnt lgkmcnt(0)
	v_lshlrev_b32_e32 v69, 16, v66
	v_pk_mul_f32 v[68:69], v[76:77], v[68:69]
	v_fma_f32 v63, v59, v70, v63
	v_add_f32_e32 v62, v62, v69
	v_add_f32_e32 v69, 1.0, v71
	v_rcp_f32_e32 v76, v69
	v_and_b32_e32 v59, 0xffff0000, v66
	v_mul_f32_e32 v62, v68, v62
	v_fma_f32 v64, v60, v70, v64
	v_pk_mul_f32 v[58:59], v[76:77], v[58:59]
	v_fmac_f32_e32 v65, v61, v70
	v_add_f32_e32 v59, v63, v59
	v_mul_f32_e32 v63, v58, v59
	v_lshlrev_b32_e32 v58, 16, v93
	v_mul_f32_e32 v59, 0xbfb8aa3b, v58
	v_exp_f32_e32 v68, v59
	v_lshlrev_b32_e32 v59, 16, v67
	v_and_b32_e32 v61, 0xffff0000, v67
	v_mul_f32_e32 v66, v63, v63
	v_add_f32_e32 v60, 1.0, v68
	v_rcp_f32_e32 v76, v60
	v_and_b32_e32 v60, 0xffff0000, v93
	v_mul_f32_e32 v68, 0xbfb8aa3b, v60
	v_exp_f32_e32 v68, v68
	v_pk_mul_f32 v[58:59], v[76:77], v[58:59]
	v_fmac_f32_e32 v66, v62, v62
	v_add_f32_e32 v59, v64, v59
	v_mul_f32_e32 v64, v58, v59
	v_add_f32_e32 v58, 1.0, v68
	v_rcp_f32_e32 v76, v58
	v_fmac_f32_e32 v66, v64, v64
	v_pk_mul_f32 v[58:59], v[76:77], v[60:61]
	s_nop 0
	v_add_f32_e32 v59, v65, v59
	v_mul_f32_e32 v58, v58, v59
	v_fmac_f32_e32 v66, v58, v58
	ds_bpermute_b32 v59, v146, v66
	v_cvt_pk_bf16_f32 v60, v62, v63
	v_cvt_pk_bf16_f32 v61, v64, v58
	s_waitcnt lgkmcnt(0)
	v_add_f32_e32 v58, v66, v59
	ds_bpermute_b32 v59, v147, v58
	global_store_dwordx2 v[78:79], v[60:61], off
	s_mov_b64 s[0:1], 0xc0000
	v_lshl_add_u64 v[78:79], v[78:79], 0, s[0:1]
	s_and_saveexec_b64 s[0:1], s[18:19]
	s_cbranch_execz .LBB0_719
	s_waitcnt lgkmcnt(0)
	v_add_f32_e32 v60, v58, v59
	global_store_dword v[90:91], v60, off offset:256
	s_branch .LBB0_719
